# device-wide barrier sites 1-4: the L1 invalidate moved to wave 1 at site entry (concurrent with wave 0's arrival/writeback/release), the in-body invalidates of leader and non-leader dropped
# speedup vs baseline: 1.0026x; 1.0026x over previous
.Lgi88_w1:
	s_mov_b64 s[6:7], exec
	v_readlane_b32 s0, v254, 8
	v_readlane_b32 s1, v254, 9
	s_and_b64 s[0:1], s[6:7], s[0:1]
	s_mov_b64 exec, s[0:1]
	s_cbranch_execz .LBB0_88
	v_readlane_b32 s0, v255, 22
	s_waitcnt vmcnt(0) expcnt(0) lgkmcnt(0)
	s_nop 0
	v_mov_b32_e32 v0, s0
	ds_read_b32 v2, v0
	v_readlane_b32 s0, v255, 23
	s_waitcnt lgkmcnt(0)
	v_cmp_ne_u32_e32 vcc, 0, v2
	v_mov_b32_e32 v0, s0
	ds_read_b32 v0, v0
	s_cbranch_vccnz .LBB0_52
	s_mov_b32 s0, 1
	s_branch .LBB0_40

.LBB0_54:
	s_or_b64 exec, exec, s[8:9]
	v_cvt_f32_u32_e32 v4, v2
	s_waitcnt vmcnt(0)
	v_readfirstlane_b32 s0, v3
	v_sub_u32_e32 v3, 0, v2
	v_rcp_iflag_f32_e32 v4, v4
	v_add_u32_e32 v5, s0, v1
	v_mul_f32_e32 v4, 0x4f7ffffe, v4
	v_cvt_u32_f32_e32 v4, v4
	v_mul_lo_u32 v1, v3, v4
	v_mul_hi_u32 v1, v4, v1
	v_add_u32_e32 v1, v4, v1
	v_mul_hi_u32 v1, v5, v1
	v_mul_lo_u32 v3, v1, v2
	v_sub_u32_e32 v3, v5, v3
	v_add_u32_e32 v4, 1, v1
	v_cmp_ge_u32_e32 vcc, v3, v2
	s_nop 1
	v_cndmask_b32_e32 v1, v1, v4, vcc
	v_sub_u32_e32 v4, v3, v2
	v_cndmask_b32_e32 v3, v3, v4, vcc
	v_add_u32_e32 v4, 1, v1
	v_cmp_ge_u32_e32 vcc, v3, v2
	v_add_u32_e32 v3, 1, v5
	s_nop 0
	v_cndmask_b32_e32 v1, v1, v4, vcc
	v_mul_lo_u32 v4, v2, v1
	v_add_u32_e32 v2, v4, v2
	v_cmp_ne_u32_e32 vcc, v3, v2
	s_and_saveexec_b64 s[0:1], vcc
	s_xor_b64 s[8:9], exec, s[0:1]
	s_cbranch_execz .LBB0_68
	v_readlane_b32 s0, v255, 20
	v_readlane_b32 s1, v255, 21
	s_waitcnt lgkmcnt(0)
	s_nop 3
	global_load_dword v0, v197, s[0:1] sc1
	s_waitcnt vmcnt(0)
	v_cmp_eq_u32_e32 vcc, v0, v1
	s_and_saveexec_b64 s[12:13], vcc
	s_cbranch_execz .LBB0_67
	s_mov_b32 s0, 1
	s_mov_b64 s[14:15], 0
	s_branch .LBB0_58

.LBB0_130:
	s_waitcnt vmcnt(0)
	s_waitcnt vmcnt(0) lgkmcnt(0)
	s_barrier
	v_readlane_b32 s0, v211, 0
	s_cmp_eq_u32 s0, 64
	s_cbranch_scc0 .Lgi182_w1
	buffer_inv sc1
	s_waitcnt vmcnt(0)
.Lgi182_w1:
	s_mov_b64 s[6:7], exec
	v_readlane_b32 s0, v254, 8
	v_readlane_b32 s1, v254, 9
	s_and_b64 s[0:1], s[6:7], s[0:1]
	s_mov_b64 exec, s[0:1]
	s_cbranch_execz .LBB0_182
	v_readlane_b32 s0, v255, 31
	s_cmp_lg_u32 s0, 0
	s_cbranch_scc1 .Lcls_chk_done
	s_and_b32 s0, s74, 7
	s_lshl_b32 s0, s0, 2
	v_mov_b32_e32 v2, s0
	s_add_u32 s2, s92, 0x5000
	s_addc_u32 s3, s93, 0
	global_load_dword v0, v2, s[2:3] sc1
	global_load_dword v1, v2, s[2:3] offset:64 sc1
	s_waitcnt vmcnt(0)
	v_add_u32_e32 v0, v0, v1
	s_nop 0
	v_readfirstlane_b32 s0, v0
	s_cmp_eq_u32 s0, 17
	s_cselect_b32 s1, 1, 0
	v_writelane_b32 v255, s1, 42
	s_cbranch_scc1 .Lcls_chk_done
	v_mov_b32_e32 v0, 1
	global_atomic_add v197, v0, s[2:3] offset:128
	s_waitcnt vmcnt(0)

.LBB0_318:
	s_waitcnt vmcnt(0)
	v_readlane_b32 s76, v255, 33
	v_readlane_b32 s78, v255, 35
	v_readlane_b32 s80, v255, 37
	v_readlane_b32 s77, v255, 34
	v_readlane_b32 s79, v255, 36
	v_readlane_b32 s81, v255, 38
	s_mov_b32 s75, s82
	s_barrier
	v_readlane_b32 s0, v211, 0
	s_cmp_eq_u32 s0, 64
	s_cbranch_scc0 .Lgi370_w1
	buffer_inv sc1
	s_waitcnt vmcnt(0)

.Lp4_nowb:
	s_waitcnt vmcnt(0)
	s_waitcnt lgkmcnt(0)
	s_barrier
	v_readlane_b32 s0, v211, 0
	s_cmp_eq_u32 s0, 64
	s_cbranch_scc0 .Lgi616_w1
	buffer_inv sc1
	s_waitcnt vmcnt(0)
